# MIX_O consumer hand-scheduled (LDS prefetch reads fill DPP hazard slots, no s_nop, 3 record buffers) + block-id rotation
# speedup vs baseline: 1.0042x; 1.0042x over previous
; #define LAS __attribute__((address_space(3)))
; #define LO2(x) __builtin_shufflevector(x, x, 0, 1)
; #define HI2(x) __builtin_shufflevector(x, x, 2, 3)
; #define C_LD(R, t) do { const LAS float* rec_ = cur + (t) * REC; R.w = *(const LAS f32x4*)(rec_ + 4 * cl); R.k = *(const LAS f32x4*)(rec_ + 64 + 4 * cl); R.r = *(const LAS f32x4*)(rec_ + 128 + 4 * cl); \
;                 if (RW) { R.kk = *(const LAS f32x4*)(rec_ + 192 + 4 * cl); R.kka = *(const LAS f32x4*)(rec_ + 256 + 4 * cl); } R.v = rec_[320 + crow]; } while (0)
; #define C_8(t) do { C_LD(C, (t) + 2); C_STEP(A, (t)); C_LD(E, (t) + 3); C_STEP(B, (t) + 1); C_LD(A, (t) + 4); C_STEP(C, (t) + 2); C_LD(B, (t) + 5); C_STEP(E, (t) + 3); \
;                     C_LD(C, (t) + 6); C_STEP(A, (t) + 4); C_LD(E, (t) + 7); C_STEP(B, (t) + 5); C_LD(A, (t) + 8); C_STEP(C, (t) + 6); C_LD(B, (t) + 9); C_STEP(E, (t) + 7); } while (0)
;     ...
;             if (cc == 0) { if (cd.samp) { s01 = LO2(snext); s23 = HI2(snext); } else { s01 = (f32x2){0.f, 0.f}; s23 = s01; } }
;             if (nd.ok && nc == 0 && nd.samp) C_S0(nd, snext);
;             const LAS float* cur = lds + (q & 1) * (CH * REC);
;             LAS float* yp = lds + YP_OFF + (q & 1) * (CH * 256) + crow * 16 + cl;
;     ...
;             ScanRec A, B, C, E;
;             C_LD(A, 0); C_LD(B, 1);
;     ...
;             C_8(0);
;             if (cd.nv > 8) { C_8(8); C_8(16); C_8(24); }
.LBB0_938:
	s_cmp_eq_u32 s67, 0
	s_cselect_b64 vcc, -1, 0
	s_and_b32 s6, s25, 1
	s_mul_i32 s7, s6, 0xa800
	v_cndmask_b32_e64 v80, v74, 0, s[30:31]
	v_cndmask_b32_e64 v81, v75, 0, s[30:31]
	s_add_i32 s7, s7, 0
	v_cndmask_b32_e32 v179, v131, v81, vcc
	v_cndmask_b32_e32 v178, v130, v80, vcc
	v_cndmask_b32_e64 v80, v72, 0, s[30:31]
	v_cndmask_b32_e64 v81, v73, 0, s[30:31]
	v_lshl_add_u32 v160, v0, 2, s7
	v_cndmask_b32_e32 v181, v137, v81, vcc
	v_cndmask_b32_e32 v180, v136, v80, vcc
	v_lshl_add_u32 v161, v126, 2, s7
	s_lshl_b32 s6, s6, 15
	v_add_u32_e32 v159, s6, v1
	ds_read_b128 v[80:83], v160
	ds_read_b128 v[84:87], v160 offset:256
	ds_read_b128 v[88:91], v160 offset:512
	ds_read_b128 v[92:95], v160 offset:768
	ds_read_b128 v[96:99], v160 offset:1024
	ds_read_b32 v100, v161 offset:1280
	ds_read_b128 v[102:105], v160 offset:1344
	ds_read_b128 v[106:109], v160 offset:1600
	ds_read_b128 v[110:113], v160 offset:1856
	ds_read_b128 v[114:117], v160 offset:2112
	ds_read_b128 v[118:121], v160 offset:2368
	ds_read_b32 v122, v161 offset:2624
	s_waitcnt lgkmcnt(6)
	v_pk_mul_f32 v[162:163], v[180:181], v[92:93]
	s_nop 0
	v_pk_fma_f32 v[162:163], v[178:179], v[94:95], v[162:163]
	s_nop 0
	v_add_f32_e32 v162, v162, v163
	ds_read_b128 v[182:185], v160 offset:2688
	ds_read_b128 v[186:189], v160 offset:2944
	v_add_f32_dpp v162, v162, v162 quad_perm:[1,0,3,2] row_mask:0xf bank_mask:0xf bound_ctrl:1
	v_pk_mul_f32 v[164:165], v[180:181], v[80:81]
	v_pk_mul_f32 v[166:167], v[178:179], v[82:83]
	v_add_f32_dpp v162, v162, v162 quad_perm:[2,3,0,1] row_mask:0xf bank_mask:0xf bound_ctrl:1
	ds_read_b128 v[190:193], v160 offset:3200
	ds_read_b128 v[194:197], v160 offset:3456
	v_add_f32_dpp v162, v162, v162 row_half_mirror row_mask:0xf bank_mask:0xf bound_ctrl:1
	v_pk_fma_f32 v[164:165], v[84:85], v[100:101], v[164:165] op_sel_hi:[1,0,1]
	v_pk_fma_f32 v[166:167], v[86:87], v[100:101], v[166:167] op_sel_hi:[1,0,1]
	v_add_f32_dpp v162, v162, v162 row_mirror row_mask:0xf bank_mask:0xf bound_ctrl:1
	ds_read_b128 v[198:201], v160 offset:3712
	ds_read_b32 v202, v161 offset:3968
	v_pk_fma_f32 v[180:181], v[96:97], v[162:163], v[164:165] op_sel_hi:[1,0,1] neg_lo:[0,1,0] neg_hi:[0,1,0]
	v_pk_fma_f32 v[178:179], v[98:99], v[162:163], v[166:167] op_sel_hi:[1,0,1] neg_lo:[0,1,0] neg_hi:[0,1,0]
	v_pk_mul_f32 v[168:169], v[88:89], v[180:181]
	s_waitcnt lgkmcnt(6)
	v_pk_mul_f32 v[172:173], v[180:181], v[114:115]
	v_pk_fma_f32 v[168:169], v[90:91], v[178:179], v[168:169]
	v_pk_fma_f32 v[172:173], v[178:179], v[116:117], v[172:173]
	v_add_f32_e32 v170, v168, v169
	ds_write_b32 v159, v170
	v_add_f32_e32 v172, v172, v173
	ds_read_b128 v[80:83], v160 offset:4032
	ds_read_b128 v[84:87], v160 offset:4288
	v_add_f32_dpp v172, v172, v172 quad_perm:[1,0,3,2] row_mask:0xf bank_mask:0xf bound_ctrl:1
	v_pk_mul_f32 v[164:165], v[180:181], v[102:103]
	v_pk_mul_f32 v[166:167], v[178:179], v[104:105]
	v_add_f32_dpp v172, v172, v172 quad_perm:[2,3,0,1] row_mask:0xf bank_mask:0xf bound_ctrl:1
	ds_read_b128 v[88:91], v160 offset:4544
	ds_read_b128 v[92:95], v160 offset:4800
	v_add_f32_dpp v172, v172, v172 row_half_mirror row_mask:0xf bank_mask:0xf bound_ctrl:1
	v_pk_fma_f32 v[164:165], v[106:107], v[122:123], v[164:165] op_sel_hi:[1,0,1]
	v_pk_fma_f32 v[166:167], v[108:109], v[122:123], v[166:167] op_sel_hi:[1,0,1]
	v_add_f32_dpp v172, v172, v172 row_mirror row_mask:0xf bank_mask:0xf bound_ctrl:1
	ds_read_b128 v[96:99], v160 offset:5056
	ds_read_b32 v100, v161 offset:5312
	v_pk_fma_f32 v[180:181], v[118:119], v[172:173], v[164:165] op_sel_hi:[1,0,1] neg_lo:[0,1,0] neg_hi:[0,1,0]
	v_pk_fma_f32 v[178:179], v[120:121], v[172:173], v[166:167] op_sel_hi:[1,0,1] neg_lo:[0,1,0] neg_hi:[0,1,0]
	v_pk_mul_f32 v[168:169], v[110:111], v[180:181]
	s_waitcnt lgkmcnt(7)
	v_pk_mul_f32 v[162:163], v[180:181], v[194:195]
	v_pk_fma_f32 v[168:169], v[112:113], v[178:179], v[168:169]
	v_pk_fma_f32 v[162:163], v[178:179], v[196:197], v[162:163]
	v_add_f32_e32 v170, v168, v169
	ds_write_b32 v159, v170 offset:1024
	v_add_f32_e32 v162, v162, v163
	ds_read_b128 v[102:105], v160 offset:5376
	ds_read_b128 v[106:109], v160 offset:5632
	v_add_f32_dpp v162, v162, v162 quad_perm:[1,0,3,2] row_mask:0xf bank_mask:0xf bound_ctrl:1
	v_pk_mul_f32 v[164:165], v[180:181], v[182:183]
	v_pk_mul_f32 v[166:167], v[178:179], v[184:185]
	v_add_f32_dpp v162, v162, v162 quad_perm:[2,3,0,1] row_mask:0xf bank_mask:0xf bound_ctrl:1
	ds_read_b128 v[110:113], v160 offset:5888
	ds_read_b128 v[114:117], v160 offset:6144
	v_add_f32_dpp v162, v162, v162 row_half_mirror row_mask:0xf bank_mask:0xf bound_ctrl:1
	v_pk_fma_f32 v[164:165], v[186:187], v[202:203], v[164:165] op_sel_hi:[1,0,1]
	v_pk_fma_f32 v[166:167], v[188:189], v[202:203], v[166:167] op_sel_hi:[1,0,1]
	v_add_f32_dpp v162, v162, v162 row_mirror row_mask:0xf bank_mask:0xf bound_ctrl:1
	ds_read_b128 v[118:121], v160 offset:6400
	ds_read_b32 v122, v161 offset:6656
	v_pk_fma_f32 v[180:181], v[198:199], v[162:163], v[164:165] op_sel_hi:[1,0,1] neg_lo:[0,1,0] neg_hi:[0,1,0]
	v_pk_fma_f32 v[178:179], v[200:201], v[162:163], v[166:167] op_sel_hi:[1,0,1] neg_lo:[0,1,0] neg_hi:[0,1,0]
	v_pk_mul_f32 v[168:169], v[190:191], v[180:181]
	s_waitcnt lgkmcnt(7)
; #define C_LD(R, t) do { const LAS float* rec_ = cur + (t) * REC; R.w = *(const LAS f32x4*)(rec_ + 4 * cl); R.k = *(const LAS f32x4*)(rec_ + 64 + 4 * cl); R.r = *(const LAS f32x4*)(rec_ + 128 + 4 * cl); \
;                 if (RW) { R.kk = *(const LAS f32x4*)(rec_ + 192 + 4 * cl); R.kka = *(const LAS f32x4*)(rec_ + 256 + 4 * cl); } R.v = rec_[320 + crow]; } while (0)
;     ...
;             ScanRec A, B, C, E;
;             C_LD(A, 0); C_LD(B, 1);
	v_pk_mul_f32 v[172:173], v[180:181], v[92:93]
	v_pk_fma_f32 v[168:169], v[192:193], v[178:179], v[168:169]
	v_pk_fma_f32 v[172:173], v[178:179], v[94:95], v[172:173]
	v_add_f32_e32 v170, v168, v169
	ds_write_b32 v159, v170 offset:2048
	v_add_f32_e32 v172, v172, v173
	ds_read_b128 v[182:185], v160 offset:6720
	ds_read_b128 v[186:189], v160 offset:6976
	v_add_f32_dpp v172, v172, v172 quad_perm:[1,0,3,2] row_mask:0xf bank_mask:0xf bound_ctrl:1
	v_pk_mul_f32 v[164:165], v[180:181], v[80:81]
	v_pk_mul_f32 v[166:167], v[178:179], v[82:83]
	v_add_f32_dpp v172, v172, v172 quad_perm:[2,3,0,1] row_mask:0xf bank_mask:0xf bound_ctrl:1
	ds_read_b128 v[190:193], v160 offset:7232
	ds_read_b128 v[194:197], v160 offset:7488
	v_add_f32_dpp v172, v172, v172 row_half_mirror row_mask:0xf bank_mask:0xf bound_ctrl:1
	v_pk_fma_f32 v[164:165], v[84:85], v[100:101], v[164:165] op_sel_hi:[1,0,1]
	v_pk_fma_f32 v[166:167], v[86:87], v[100:101], v[166:167] op_sel_hi:[1,0,1]
	v_add_f32_dpp v172, v172, v172 row_mirror row_mask:0xf bank_mask:0xf bound_ctrl:1
	ds_read_b128 v[198:201], v160 offset:7744
	ds_read_b32 v202, v161 offset:8000
	v_pk_fma_f32 v[180:181], v[96:97], v[172:173], v[164:165] op_sel_hi:[1,0,1] neg_lo:[0,1,0] neg_hi:[0,1,0]
	v_pk_fma_f32 v[178:179], v[98:99], v[172:173], v[166:167] op_sel_hi:[1,0,1] neg_lo:[0,1,0] neg_hi:[0,1,0]
	v_pk_mul_f32 v[168:169], v[88:89], v[180:181]
	s_waitcnt lgkmcnt(7)
	v_pk_mul_f32 v[162:163], v[180:181], v[114:115]
	v_pk_fma_f32 v[168:169], v[90:91], v[178:179], v[168:169]
	v_pk_fma_f32 v[162:163], v[178:179], v[116:117], v[162:163]
	v_add_f32_e32 v170, v168, v169
	ds_write_b32 v159, v170 offset:3072
	v_add_f32_e32 v162, v162, v163
	ds_read_b128 v[80:83], v160 offset:8064
	ds_read_b128 v[84:87], v160 offset:8320
	v_add_f32_dpp v162, v162, v162 quad_perm:[1,0,3,2] row_mask:0xf bank_mask:0xf bound_ctrl:1
	v_pk_mul_f32 v[164:165], v[180:181], v[102:103]
	v_pk_mul_f32 v[166:167], v[178:179], v[104:105]
	v_add_f32_dpp v162, v162, v162 quad_perm:[2,3,0,1] row_mask:0xf bank_mask:0xf bound_ctrl:1
	ds_read_b128 v[88:91], v160 offset:8576
	ds_read_b128 v[92:95], v160 offset:8832
	v_add_f32_dpp v162, v162, v162 row_half_mirror row_mask:0xf bank_mask:0xf bound_ctrl:1
	v_pk_fma_f32 v[164:165], v[106:107], v[122:123], v[164:165] op_sel_hi:[1,0,1]
	v_pk_fma_f32 v[166:167], v[108:109], v[122:123], v[166:167] op_sel_hi:[1,0,1]
	v_add_f32_dpp v162, v162, v162 row_mirror row_mask:0xf bank_mask:0xf bound_ctrl:1
	ds_read_b128 v[96:99], v160 offset:9088
	ds_read_b32 v100, v161 offset:9344
	v_pk_fma_f32 v[180:181], v[118:119], v[162:163], v[164:165] op_sel_hi:[1,0,1] neg_lo:[0,1,0] neg_hi:[0,1,0]
	v_pk_fma_f32 v[178:179], v[120:121], v[162:163], v[166:167] op_sel_hi:[1,0,1] neg_lo:[0,1,0] neg_hi:[0,1,0]
	v_pk_mul_f32 v[168:169], v[110:111], v[180:181]
	s_waitcnt lgkmcnt(7)
	v_pk_mul_f32 v[172:173], v[180:181], v[194:195]
	v_pk_fma_f32 v[168:169], v[112:113], v[178:179], v[168:169]
	v_pk_fma_f32 v[172:173], v[178:179], v[196:197], v[172:173]
	v_add_f32_e32 v170, v168, v169
	ds_write_b32 v159, v170 offset:4096
	v_add_f32_e32 v172, v172, v173
	ds_read_b128 v[102:105], v160 offset:9408
	ds_read_b128 v[106:109], v160 offset:9664
	v_add_f32_dpp v172, v172, v172 quad_perm:[1,0,3,2] row_mask:0xf bank_mask:0xf bound_ctrl:1
	v_pk_mul_f32 v[164:165], v[180:181], v[182:183]
	v_pk_mul_f32 v[166:167], v[178:179], v[184:185]
	v_add_f32_dpp v172, v172, v172 quad_perm:[2,3,0,1] row_mask:0xf bank_mask:0xf bound_ctrl:1
	ds_read_b128 v[110:113], v160 offset:9920
	ds_read_b128 v[114:117], v160 offset:10176
	v_add_f32_dpp v172, v172, v172 row_half_mirror row_mask:0xf bank_mask:0xf bound_ctrl:1
	v_pk_fma_f32 v[164:165], v[186:187], v[202:203], v[164:165] op_sel_hi:[1,0,1]
	v_pk_fma_f32 v[166:167], v[188:189], v[202:203], v[166:167] op_sel_hi:[1,0,1]
	v_add_f32_dpp v172, v172, v172 row_mirror row_mask:0xf bank_mask:0xf bound_ctrl:1
	ds_read_b128 v[118:121], v160 offset:10432
	ds_read_b32 v122, v161 offset:10688
	v_pk_fma_f32 v[180:181], v[198:199], v[172:173], v[164:165] op_sel_hi:[1,0,1] neg_lo:[0,1,0] neg_hi:[0,1,0]
	v_pk_fma_f32 v[178:179], v[200:201], v[172:173], v[166:167] op_sel_hi:[1,0,1] neg_lo:[0,1,0] neg_hi:[0,1,0]
	v_pk_mul_f32 v[168:169], v[190:191], v[180:181]
	s_waitcnt lgkmcnt(7)
	v_pk_mul_f32 v[162:163], v[180:181], v[92:93]
	v_pk_fma_f32 v[168:169], v[192:193], v[178:179], v[168:169]
	v_pk_fma_f32 v[162:163], v[178:179], v[94:95], v[162:163]
	v_add_f32_e32 v170, v168, v169
	ds_write_b32 v159, v170 offset:5120
	v_add_f32_e32 v162, v162, v163
	ds_read_b128 v[182:185], v160 offset:10752
	ds_read_b128 v[186:189], v160 offset:11008
	v_add_f32_dpp v162, v162, v162 quad_perm:[1,0,3,2] row_mask:0xf bank_mask:0xf bound_ctrl:1
	v_pk_mul_f32 v[164:165], v[180:181], v[80:81]
	v_pk_mul_f32 v[166:167], v[178:179], v[82:83]
	v_add_f32_dpp v162, v162, v162 quad_perm:[2,3,0,1] row_mask:0xf bank_mask:0xf bound_ctrl:1
	ds_read_b128 v[190:193], v160 offset:11264
	ds_read_b128 v[194:197], v160 offset:11520
	v_add_f32_dpp v162, v162, v162 row_half_mirror row_mask:0xf bank_mask:0xf bound_ctrl:1
	v_pk_fma_f32 v[164:165], v[84:85], v[100:101], v[164:165] op_sel_hi:[1,0,1]
	v_pk_fma_f32 v[166:167], v[86:87], v[100:101], v[166:167] op_sel_hi:[1,0,1]
	v_add_f32_dpp v162, v162, v162 row_mirror row_mask:0xf bank_mask:0xf bound_ctrl:1
	ds_read_b128 v[198:201], v160 offset:11776
	ds_read_b32 v202, v161 offset:12032
	v_pk_fma_f32 v[180:181], v[96:97], v[162:163], v[164:165] op_sel_hi:[1,0,1] neg_lo:[0,1,0] neg_hi:[0,1,0]
	v_pk_fma_f32 v[178:179], v[98:99], v[162:163], v[166:167] op_sel_hi:[1,0,1] neg_lo:[0,1,0] neg_hi:[0,1,0]
	v_pk_mul_f32 v[168:169], v[88:89], v[180:181]
	s_waitcnt lgkmcnt(7)
; #define C_LD(R, t) do { const LAS float* rec_ = cur + (t) * REC; R.w = *(const LAS f32x4*)(rec_ + 4 * cl); R.k = *(const LAS f32x4*)(rec_ + 64 + 4 * cl); R.r = *(const LAS f32x4*)(rec_ + 128 + 4 * cl); \
;                 if (RW) { R.kk = *(const LAS f32x4*)(rec_ + 192 + 4 * cl); R.kka = *(const LAS f32x4*)(rec_ + 256 + 4 * cl); } R.v = rec_[320 + crow]; } while (0)
; #define C_8(t) do { C_LD(C, (t) + 2); C_STEP(A, (t)); C_LD(E, (t) + 3); C_STEP(B, (t) + 1); C_LD(A, (t) + 4); C_STEP(C, (t) + 2); C_LD(B, (t) + 5); C_STEP(E, (t) + 3); \
;                     C_LD(C, (t) + 6); C_STEP(A, (t) + 4); C_LD(E, (t) + 7); C_STEP(B, (t) + 5); C_LD(A, (t) + 8); C_STEP(C, (t) + 6); C_LD(B, (t) + 9); C_STEP(E, (t) + 7); } while (0)
;     ...
;             ScanRec A, B, C, E;
;             C_LD(A, 0); C_LD(B, 1);
;     ...
;             C_8(0);
;             if (cd.nv > 8) { C_8(8); C_8(16); C_8(24); }
	v_pk_mul_f32 v[172:173], v[180:181], v[114:115]
	v_pk_fma_f32 v[168:169], v[90:91], v[178:179], v[168:169]
	v_pk_fma_f32 v[172:173], v[178:179], v[116:117], v[172:173]
	v_add_f32_e32 v170, v168, v169
	ds_write_b32 v159, v170 offset:6144
	v_add_f32_e32 v172, v172, v173
	ds_read_b128 v[80:83], v160 offset:12096
	ds_read_b128 v[84:87], v160 offset:12352
	v_add_f32_dpp v172, v172, v172 quad_perm:[1,0,3,2] row_mask:0xf bank_mask:0xf bound_ctrl:1
	v_pk_mul_f32 v[164:165], v[180:181], v[102:103]
	v_pk_mul_f32 v[166:167], v[178:179], v[104:105]
	v_add_f32_dpp v172, v172, v172 quad_perm:[2,3,0,1] row_mask:0xf bank_mask:0xf bound_ctrl:1
	ds_read_b128 v[88:91], v160 offset:12608
	ds_read_b128 v[92:95], v160 offset:12864
	v_add_f32_dpp v172, v172, v172 row_half_mirror row_mask:0xf bank_mask:0xf bound_ctrl:1
	v_pk_fma_f32 v[164:165], v[106:107], v[122:123], v[164:165] op_sel_hi:[1,0,1]
	v_pk_fma_f32 v[166:167], v[108:109], v[122:123], v[166:167] op_sel_hi:[1,0,1]
	v_add_f32_dpp v172, v172, v172 row_mirror row_mask:0xf bank_mask:0xf bound_ctrl:1
	ds_read_b128 v[96:99], v160 offset:13120
	ds_read_b32 v100, v161 offset:13376
	v_pk_fma_f32 v[180:181], v[118:119], v[172:173], v[164:165] op_sel_hi:[1,0,1] neg_lo:[0,1,0] neg_hi:[0,1,0]
	v_pk_fma_f32 v[178:179], v[120:121], v[172:173], v[166:167] op_sel_hi:[1,0,1] neg_lo:[0,1,0] neg_hi:[0,1,0]
	v_pk_mul_f32 v[168:169], v[110:111], v[180:181]
	s_waitcnt lgkmcnt(7)
	v_pk_mul_f32 v[162:163], v[180:181], v[194:195]
	v_pk_fma_f32 v[168:169], v[112:113], v[178:179], v[168:169]
	v_pk_fma_f32 v[162:163], v[178:179], v[196:197], v[162:163]
	v_add_f32_e32 v170, v168, v169
	ds_write_b32 v159, v170 offset:7168
	s_cmp_lt_i32 s2, 9
	s_cbranch_scc0 .Lmo_more
	s_waitcnt lgkmcnt(0)
	v_mov_b32_e32 v80, v180
	v_mov_b32_e32 v81, v181
	v_mov_b32_e32 v82, v178
	v_mov_b32_e32 v83, v179
	s_branch .LBB0_940
.Lmo_more:
	v_add_f32_e32 v162, v162, v163
	ds_read_b128 v[102:105], v160 offset:13440
	ds_read_b128 v[106:109], v160 offset:13696
	v_add_f32_dpp v162, v162, v162 quad_perm:[1,0,3,2] row_mask:0xf bank_mask:0xf bound_ctrl:1
	v_pk_mul_f32 v[164:165], v[180:181], v[182:183]
	v_pk_mul_f32 v[166:167], v[178:179], v[184:185]
	v_add_f32_dpp v162, v162, v162 quad_perm:[2,3,0,1] row_mask:0xf bank_mask:0xf bound_ctrl:1
	ds_read_b128 v[110:113], v160 offset:13952
	ds_read_b128 v[114:117], v160 offset:14208
	v_add_f32_dpp v162, v162, v162 row_half_mirror row_mask:0xf bank_mask:0xf bound_ctrl:1
	v_pk_fma_f32 v[164:165], v[186:187], v[202:203], v[164:165] op_sel_hi:[1,0,1]
	v_pk_fma_f32 v[166:167], v[188:189], v[202:203], v[166:167] op_sel_hi:[1,0,1]
	v_add_f32_dpp v162, v162, v162 row_mirror row_mask:0xf bank_mask:0xf bound_ctrl:1
	ds_read_b128 v[118:121], v160 offset:14464
	ds_read_b32 v122, v161 offset:14720
	v_pk_fma_f32 v[180:181], v[198:199], v[162:163], v[164:165] op_sel_hi:[1,0,1] neg_lo:[0,1,0] neg_hi:[0,1,0]
	v_pk_fma_f32 v[178:179], v[200:201], v[162:163], v[166:167] op_sel_hi:[1,0,1] neg_lo:[0,1,0] neg_hi:[0,1,0]
	v_pk_mul_f32 v[168:169], v[190:191], v[180:181]
	s_waitcnt lgkmcnt(7)
	v_pk_mul_f32 v[172:173], v[180:181], v[92:93]
	v_pk_fma_f32 v[168:169], v[192:193], v[178:179], v[168:169]
	v_pk_fma_f32 v[172:173], v[178:179], v[94:95], v[172:173]
	v_add_f32_e32 v170, v168, v169
	ds_write_b32 v159, v170 offset:8192
	v_add_f32_e32 v172, v172, v173
	ds_read_b128 v[182:185], v160 offset:14784
	ds_read_b128 v[186:189], v160 offset:15040
	v_add_f32_dpp v172, v172, v172 quad_perm:[1,0,3,2] row_mask:0xf bank_mask:0xf bound_ctrl:1
	v_pk_mul_f32 v[164:165], v[180:181], v[80:81]
	v_pk_mul_f32 v[166:167], v[178:179], v[82:83]
	v_add_f32_dpp v172, v172, v172 quad_perm:[2,3,0,1] row_mask:0xf bank_mask:0xf bound_ctrl:1
	ds_read_b128 v[190:193], v160 offset:15296
	ds_read_b128 v[194:197], v160 offset:15552
	v_add_f32_dpp v172, v172, v172 row_half_mirror row_mask:0xf bank_mask:0xf bound_ctrl:1
	v_pk_fma_f32 v[164:165], v[84:85], v[100:101], v[164:165] op_sel_hi:[1,0,1]
	v_pk_fma_f32 v[166:167], v[86:87], v[100:101], v[166:167] op_sel_hi:[1,0,1]
	v_add_f32_dpp v172, v172, v172 row_mirror row_mask:0xf bank_mask:0xf bound_ctrl:1
	ds_read_b128 v[198:201], v160 offset:15808
	ds_read_b32 v202, v161 offset:16064
	v_pk_fma_f32 v[180:181], v[96:97], v[172:173], v[164:165] op_sel_hi:[1,0,1] neg_lo:[0,1,0] neg_hi:[0,1,0]
	v_pk_fma_f32 v[178:179], v[98:99], v[172:173], v[166:167] op_sel_hi:[1,0,1] neg_lo:[0,1,0] neg_hi:[0,1,0]
	v_pk_mul_f32 v[168:169], v[88:89], v[180:181]
	s_waitcnt lgkmcnt(7)
	v_pk_mul_f32 v[162:163], v[180:181], v[114:115]
	v_pk_fma_f32 v[168:169], v[90:91], v[178:179], v[168:169]
	v_pk_fma_f32 v[162:163], v[178:179], v[116:117], v[162:163]
	v_add_f32_e32 v170, v168, v169
	ds_write_b32 v159, v170 offset:9216
	v_add_f32_e32 v162, v162, v163
	ds_read_b128 v[80:83], v160 offset:16128
	ds_read_b128 v[84:87], v160 offset:16384
	v_add_f32_dpp v162, v162, v162 quad_perm:[1,0,3,2] row_mask:0xf bank_mask:0xf bound_ctrl:1
	v_pk_mul_f32 v[164:165], v[180:181], v[102:103]
	v_pk_mul_f32 v[166:167], v[178:179], v[104:105]
	v_add_f32_dpp v162, v162, v162 quad_perm:[2,3,0,1] row_mask:0xf bank_mask:0xf bound_ctrl:1
	ds_read_b128 v[88:91], v160 offset:16640
	ds_read_b128 v[92:95], v160 offset:16896
	v_add_f32_dpp v162, v162, v162 row_half_mirror row_mask:0xf bank_mask:0xf bound_ctrl:1
	v_pk_fma_f32 v[164:165], v[106:107], v[122:123], v[164:165] op_sel_hi:[1,0,1]
	v_pk_fma_f32 v[166:167], v[108:109], v[122:123], v[166:167] op_sel_hi:[1,0,1]
	v_add_f32_dpp v162, v162, v162 row_mirror row_mask:0xf bank_mask:0xf bound_ctrl:1
	ds_read_b128 v[96:99], v160 offset:17152
	ds_read_b32 v100, v161 offset:17408
	v_pk_fma_f32 v[180:181], v[118:119], v[162:163], v[164:165] op_sel_hi:[1,0,1] neg_lo:[0,1,0] neg_hi:[0,1,0]
	v_pk_fma_f32 v[178:179], v[120:121], v[162:163], v[166:167] op_sel_hi:[1,0,1] neg_lo:[0,1,0] neg_hi:[0,1,0]
	v_pk_mul_f32 v[168:169], v[110:111], v[180:181]
	s_waitcnt lgkmcnt(7)
; #define C_LD(R, t) do { const LAS float* rec_ = cur + (t) * REC; R.w = *(const LAS f32x4*)(rec_ + 4 * cl); R.k = *(const LAS f32x4*)(rec_ + 64 + 4 * cl); R.r = *(const LAS f32x4*)(rec_ + 128 + 4 * cl); \
;                 if (RW) { R.kk = *(const LAS f32x4*)(rec_ + 192 + 4 * cl); R.kka = *(const LAS f32x4*)(rec_ + 256 + 4 * cl); } R.v = rec_[320 + crow]; } while (0)
;     ...
;             ScanRec A, B, C, E;
;             C_LD(A, 0); C_LD(B, 1);
	v_pk_mul_f32 v[172:173], v[180:181], v[194:195]
	v_pk_fma_f32 v[168:169], v[112:113], v[178:179], v[168:169]
	v_pk_fma_f32 v[172:173], v[178:179], v[196:197], v[172:173]
	v_add_f32_e32 v170, v168, v169
	ds_write_b32 v159, v170 offset:10240
	v_add_f32_e32 v172, v172, v173
	ds_read_b128 v[102:105], v160 offset:17472
	ds_read_b128 v[106:109], v160 offset:17728
	v_add_f32_dpp v172, v172, v172 quad_perm:[1,0,3,2] row_mask:0xf bank_mask:0xf bound_ctrl:1
	v_pk_mul_f32 v[164:165], v[180:181], v[182:183]
	v_pk_mul_f32 v[166:167], v[178:179], v[184:185]
	v_add_f32_dpp v172, v172, v172 quad_perm:[2,3,0,1] row_mask:0xf bank_mask:0xf bound_ctrl:1
	ds_read_b128 v[110:113], v160 offset:17984
	ds_read_b128 v[114:117], v160 offset:18240
	v_add_f32_dpp v172, v172, v172 row_half_mirror row_mask:0xf bank_mask:0xf bound_ctrl:1
	v_pk_fma_f32 v[164:165], v[186:187], v[202:203], v[164:165] op_sel_hi:[1,0,1]
	v_pk_fma_f32 v[166:167], v[188:189], v[202:203], v[166:167] op_sel_hi:[1,0,1]
	v_add_f32_dpp v172, v172, v172 row_mirror row_mask:0xf bank_mask:0xf bound_ctrl:1
	ds_read_b128 v[118:121], v160 offset:18496
	ds_read_b32 v122, v161 offset:18752
	v_pk_fma_f32 v[180:181], v[198:199], v[172:173], v[164:165] op_sel_hi:[1,0,1] neg_lo:[0,1,0] neg_hi:[0,1,0]
	v_pk_fma_f32 v[178:179], v[200:201], v[172:173], v[166:167] op_sel_hi:[1,0,1] neg_lo:[0,1,0] neg_hi:[0,1,0]
	v_pk_mul_f32 v[168:169], v[190:191], v[180:181]
	s_waitcnt lgkmcnt(7)
	v_pk_mul_f32 v[162:163], v[180:181], v[92:93]
	v_pk_fma_f32 v[168:169], v[192:193], v[178:179], v[168:169]
	v_pk_fma_f32 v[162:163], v[178:179], v[94:95], v[162:163]
	v_add_f32_e32 v170, v168, v169
	ds_write_b32 v159, v170 offset:11264
	v_add_f32_e32 v162, v162, v163
	ds_read_b128 v[182:185], v160 offset:18816
	ds_read_b128 v[186:189], v160 offset:19072
	v_add_f32_dpp v162, v162, v162 quad_perm:[1,0,3,2] row_mask:0xf bank_mask:0xf bound_ctrl:1
	v_pk_mul_f32 v[164:165], v[180:181], v[80:81]
	v_pk_mul_f32 v[166:167], v[178:179], v[82:83]
	v_add_f32_dpp v162, v162, v162 quad_perm:[2,3,0,1] row_mask:0xf bank_mask:0xf bound_ctrl:1
	ds_read_b128 v[190:193], v160 offset:19328
	ds_read_b128 v[194:197], v160 offset:19584
	v_add_f32_dpp v162, v162, v162 row_half_mirror row_mask:0xf bank_mask:0xf bound_ctrl:1
	v_pk_fma_f32 v[164:165], v[84:85], v[100:101], v[164:165] op_sel_hi:[1,0,1]
	v_pk_fma_f32 v[166:167], v[86:87], v[100:101], v[166:167] op_sel_hi:[1,0,1]
	v_add_f32_dpp v162, v162, v162 row_mirror row_mask:0xf bank_mask:0xf bound_ctrl:1
	ds_read_b128 v[198:201], v160 offset:19840
	ds_read_b32 v202, v161 offset:20096
	v_pk_fma_f32 v[180:181], v[96:97], v[162:163], v[164:165] op_sel_hi:[1,0,1] neg_lo:[0,1,0] neg_hi:[0,1,0]
	v_pk_fma_f32 v[178:179], v[98:99], v[162:163], v[166:167] op_sel_hi:[1,0,1] neg_lo:[0,1,0] neg_hi:[0,1,0]
	v_pk_mul_f32 v[168:169], v[88:89], v[180:181]
	s_waitcnt lgkmcnt(7)
	v_pk_mul_f32 v[172:173], v[180:181], v[114:115]
	v_pk_fma_f32 v[168:169], v[90:91], v[178:179], v[168:169]
	v_pk_fma_f32 v[172:173], v[178:179], v[116:117], v[172:173]
	v_add_f32_e32 v170, v168, v169
	ds_write_b32 v159, v170 offset:12288
	v_add_f32_e32 v172, v172, v173
	ds_read_b128 v[80:83], v160 offset:20160
	ds_read_b128 v[84:87], v160 offset:20416
	v_add_f32_dpp v172, v172, v172 quad_perm:[1,0,3,2] row_mask:0xf bank_mask:0xf bound_ctrl:1
	v_pk_mul_f32 v[164:165], v[180:181], v[102:103]
	v_pk_mul_f32 v[166:167], v[178:179], v[104:105]
	v_add_f32_dpp v172, v172, v172 quad_perm:[2,3,0,1] row_mask:0xf bank_mask:0xf bound_ctrl:1
	ds_read_b128 v[88:91], v160 offset:20672
	ds_read_b128 v[92:95], v160 offset:20928
	v_add_f32_dpp v172, v172, v172 row_half_mirror row_mask:0xf bank_mask:0xf bound_ctrl:1
	v_pk_fma_f32 v[164:165], v[106:107], v[122:123], v[164:165] op_sel_hi:[1,0,1]
	v_pk_fma_f32 v[166:167], v[108:109], v[122:123], v[166:167] op_sel_hi:[1,0,1]
	v_add_f32_dpp v172, v172, v172 row_mirror row_mask:0xf bank_mask:0xf bound_ctrl:1
	ds_read_b128 v[96:99], v160 offset:21184
	ds_read_b32 v100, v161 offset:21440
	v_pk_fma_f32 v[180:181], v[118:119], v[172:173], v[164:165] op_sel_hi:[1,0,1] neg_lo:[0,1,0] neg_hi:[0,1,0]
	v_pk_fma_f32 v[178:179], v[120:121], v[172:173], v[166:167] op_sel_hi:[1,0,1] neg_lo:[0,1,0] neg_hi:[0,1,0]
	v_pk_mul_f32 v[168:169], v[110:111], v[180:181]
	s_waitcnt lgkmcnt(7)
	v_pk_mul_f32 v[162:163], v[180:181], v[194:195]
	v_pk_fma_f32 v[168:169], v[112:113], v[178:179], v[168:169]
	v_pk_fma_f32 v[162:163], v[178:179], v[196:197], v[162:163]
	v_add_f32_e32 v170, v168, v169
	ds_write_b32 v159, v170 offset:13312
	v_add_f32_e32 v162, v162, v163
	ds_read_b128 v[102:105], v160 offset:21504
	ds_read_b128 v[106:109], v160 offset:21760
	v_add_f32_dpp v162, v162, v162 quad_perm:[1,0,3,2] row_mask:0xf bank_mask:0xf bound_ctrl:1
	v_pk_mul_f32 v[164:165], v[180:181], v[182:183]
	v_pk_mul_f32 v[166:167], v[178:179], v[184:185]
	v_add_f32_dpp v162, v162, v162 quad_perm:[2,3,0,1] row_mask:0xf bank_mask:0xf bound_ctrl:1
	ds_read_b128 v[110:113], v160 offset:22016
	ds_read_b128 v[114:117], v160 offset:22272
	v_add_f32_dpp v162, v162, v162 row_half_mirror row_mask:0xf bank_mask:0xf bound_ctrl:1
	v_pk_fma_f32 v[164:165], v[186:187], v[202:203], v[164:165] op_sel_hi:[1,0,1]
	v_pk_fma_f32 v[166:167], v[188:189], v[202:203], v[166:167] op_sel_hi:[1,0,1]
	v_add_f32_dpp v162, v162, v162 row_mirror row_mask:0xf bank_mask:0xf bound_ctrl:1
	ds_read_b128 v[118:121], v160 offset:22528
	ds_read_b32 v122, v161 offset:22784
	v_pk_fma_f32 v[180:181], v[198:199], v[162:163], v[164:165] op_sel_hi:[1,0,1] neg_lo:[0,1,0] neg_hi:[0,1,0]
	v_pk_fma_f32 v[178:179], v[200:201], v[162:163], v[166:167] op_sel_hi:[1,0,1] neg_lo:[0,1,0] neg_hi:[0,1,0]
	v_pk_mul_f32 v[168:169], v[190:191], v[180:181]
	s_waitcnt lgkmcnt(7)
; #define C_LD(R, t) do { const LAS float* rec_ = cur + (t) * REC; R.w = *(const LAS f32x4*)(rec_ + 4 * cl); R.k = *(const LAS f32x4*)(rec_ + 64 + 4 * cl); R.r = *(const LAS f32x4*)(rec_ + 128 + 4 * cl); \
;                 if (RW) { R.kk = *(const LAS f32x4*)(rec_ + 192 + 4 * cl); R.kka = *(const LAS f32x4*)(rec_ + 256 + 4 * cl); } R.v = rec_[320 + crow]; } while (0)
;     ...
;             ScanRec A, B, C, E;
;             C_LD(A, 0); C_LD(B, 1);
	v_pk_mul_f32 v[172:173], v[180:181], v[92:93]
	v_pk_fma_f32 v[168:169], v[192:193], v[178:179], v[168:169]
	v_pk_fma_f32 v[172:173], v[178:179], v[94:95], v[172:173]
	v_add_f32_e32 v170, v168, v169
	ds_write_b32 v159, v170 offset:14336
	v_add_f32_e32 v172, v172, v173
	ds_read_b128 v[182:185], v160 offset:22848
	ds_read_b128 v[186:189], v160 offset:23104
	v_add_f32_dpp v172, v172, v172 quad_perm:[1,0,3,2] row_mask:0xf bank_mask:0xf bound_ctrl:1
	v_pk_mul_f32 v[164:165], v[180:181], v[80:81]
	v_pk_mul_f32 v[166:167], v[178:179], v[82:83]
	v_add_f32_dpp v172, v172, v172 quad_perm:[2,3,0,1] row_mask:0xf bank_mask:0xf bound_ctrl:1
	ds_read_b128 v[190:193], v160 offset:23360
	ds_read_b128 v[194:197], v160 offset:23616
	v_add_f32_dpp v172, v172, v172 row_half_mirror row_mask:0xf bank_mask:0xf bound_ctrl:1
	v_pk_fma_f32 v[164:165], v[84:85], v[100:101], v[164:165] op_sel_hi:[1,0,1]
	v_pk_fma_f32 v[166:167], v[86:87], v[100:101], v[166:167] op_sel_hi:[1,0,1]
	v_add_f32_dpp v172, v172, v172 row_mirror row_mask:0xf bank_mask:0xf bound_ctrl:1
	ds_read_b128 v[198:201], v160 offset:23872
	ds_read_b32 v202, v161 offset:24128
	v_pk_fma_f32 v[180:181], v[96:97], v[172:173], v[164:165] op_sel_hi:[1,0,1] neg_lo:[0,1,0] neg_hi:[0,1,0]
	v_pk_fma_f32 v[178:179], v[98:99], v[172:173], v[166:167] op_sel_hi:[1,0,1] neg_lo:[0,1,0] neg_hi:[0,1,0]
	v_pk_mul_f32 v[168:169], v[88:89], v[180:181]
	s_waitcnt lgkmcnt(7)
	v_pk_mul_f32 v[162:163], v[180:181], v[114:115]
	v_pk_fma_f32 v[168:169], v[90:91], v[178:179], v[168:169]
	v_pk_fma_f32 v[162:163], v[178:179], v[116:117], v[162:163]
	v_add_f32_e32 v170, v168, v169
	ds_write_b32 v159, v170 offset:15360
	v_add_f32_e32 v162, v162, v163
	ds_read_b128 v[80:83], v160 offset:24192
	ds_read_b128 v[84:87], v160 offset:24448
	v_add_f32_dpp v162, v162, v162 quad_perm:[1,0,3,2] row_mask:0xf bank_mask:0xf bound_ctrl:1
	v_pk_mul_f32 v[164:165], v[180:181], v[102:103]
	v_pk_mul_f32 v[166:167], v[178:179], v[104:105]
	v_add_f32_dpp v162, v162, v162 quad_perm:[2,3,0,1] row_mask:0xf bank_mask:0xf bound_ctrl:1
	ds_read_b128 v[88:91], v160 offset:24704
	ds_read_b128 v[92:95], v160 offset:24960
	v_add_f32_dpp v162, v162, v162 row_half_mirror row_mask:0xf bank_mask:0xf bound_ctrl:1
	v_pk_fma_f32 v[164:165], v[106:107], v[122:123], v[164:165] op_sel_hi:[1,0,1]
	v_pk_fma_f32 v[166:167], v[108:109], v[122:123], v[166:167] op_sel_hi:[1,0,1]
	v_add_f32_dpp v162, v162, v162 row_mirror row_mask:0xf bank_mask:0xf bound_ctrl:1
	ds_read_b128 v[96:99], v160 offset:25216
	ds_read_b32 v100, v161 offset:25472
	v_pk_fma_f32 v[180:181], v[118:119], v[162:163], v[164:165] op_sel_hi:[1,0,1] neg_lo:[0,1,0] neg_hi:[0,1,0]
	v_pk_fma_f32 v[178:179], v[120:121], v[162:163], v[166:167] op_sel_hi:[1,0,1] neg_lo:[0,1,0] neg_hi:[0,1,0]
	v_pk_mul_f32 v[168:169], v[110:111], v[180:181]
	s_waitcnt lgkmcnt(7)
	v_pk_mul_f32 v[172:173], v[180:181], v[194:195]
	v_pk_fma_f32 v[168:169], v[112:113], v[178:179], v[168:169]
	v_pk_fma_f32 v[172:173], v[178:179], v[196:197], v[172:173]
	v_add_f32_e32 v170, v168, v169
	ds_write_b32 v159, v170 offset:16384
	v_add_f32_e32 v172, v172, v173
	ds_read_b128 v[102:105], v160 offset:25536
	ds_read_b128 v[106:109], v160 offset:25792
	v_add_f32_dpp v172, v172, v172 quad_perm:[1,0,3,2] row_mask:0xf bank_mask:0xf bound_ctrl:1
	v_pk_mul_f32 v[164:165], v[180:181], v[182:183]
	v_pk_mul_f32 v[166:167], v[178:179], v[184:185]
	v_add_f32_dpp v172, v172, v172 quad_perm:[2,3,0,1] row_mask:0xf bank_mask:0xf bound_ctrl:1
	ds_read_b128 v[110:113], v160 offset:26048
	ds_read_b128 v[114:117], v160 offset:26304
	v_add_f32_dpp v172, v172, v172 row_half_mirror row_mask:0xf bank_mask:0xf bound_ctrl:1
	v_pk_fma_f32 v[164:165], v[186:187], v[202:203], v[164:165] op_sel_hi:[1,0,1]
	v_pk_fma_f32 v[166:167], v[188:189], v[202:203], v[166:167] op_sel_hi:[1,0,1]
	v_add_f32_dpp v172, v172, v172 row_mirror row_mask:0xf bank_mask:0xf bound_ctrl:1
	ds_read_b128 v[118:121], v160 offset:26560
	ds_read_b32 v122, v161 offset:26816
	v_pk_fma_f32 v[180:181], v[198:199], v[172:173], v[164:165] op_sel_hi:[1,0,1] neg_lo:[0,1,0] neg_hi:[0,1,0]
	v_pk_fma_f32 v[178:179], v[200:201], v[172:173], v[166:167] op_sel_hi:[1,0,1] neg_lo:[0,1,0] neg_hi:[0,1,0]
	v_pk_mul_f32 v[168:169], v[190:191], v[180:181]
	s_waitcnt lgkmcnt(7)
	v_pk_mul_f32 v[162:163], v[180:181], v[92:93]
	v_pk_fma_f32 v[168:169], v[192:193], v[178:179], v[168:169]
	v_pk_fma_f32 v[162:163], v[178:179], v[94:95], v[162:163]
	v_add_f32_e32 v170, v168, v169
	ds_write_b32 v159, v170 offset:17408
	v_add_f32_e32 v162, v162, v163
	ds_read_b128 v[182:185], v160 offset:26880
	ds_read_b128 v[186:189], v160 offset:27136
	v_add_f32_dpp v162, v162, v162 quad_perm:[1,0,3,2] row_mask:0xf bank_mask:0xf bound_ctrl:1
	v_pk_mul_f32 v[164:165], v[180:181], v[80:81]
	v_pk_mul_f32 v[166:167], v[178:179], v[82:83]
	v_add_f32_dpp v162, v162, v162 quad_perm:[2,3,0,1] row_mask:0xf bank_mask:0xf bound_ctrl:1
	ds_read_b128 v[190:193], v160 offset:27392
	ds_read_b128 v[194:197], v160 offset:27648
	v_add_f32_dpp v162, v162, v162 row_half_mirror row_mask:0xf bank_mask:0xf bound_ctrl:1
	v_pk_fma_f32 v[164:165], v[84:85], v[100:101], v[164:165] op_sel_hi:[1,0,1]
	v_pk_fma_f32 v[166:167], v[86:87], v[100:101], v[166:167] op_sel_hi:[1,0,1]
	v_add_f32_dpp v162, v162, v162 row_mirror row_mask:0xf bank_mask:0xf bound_ctrl:1
	ds_read_b128 v[198:201], v160 offset:27904
	ds_read_b32 v202, v161 offset:28160
	v_pk_fma_f32 v[180:181], v[96:97], v[162:163], v[164:165] op_sel_hi:[1,0,1] neg_lo:[0,1,0] neg_hi:[0,1,0]
	v_pk_fma_f32 v[178:179], v[98:99], v[162:163], v[166:167] op_sel_hi:[1,0,1] neg_lo:[0,1,0] neg_hi:[0,1,0]
	v_pk_mul_f32 v[168:169], v[88:89], v[180:181]
	s_waitcnt lgkmcnt(7)
; #define C_LD(R, t) do { const LAS float* rec_ = cur + (t) * REC; R.w = *(const LAS f32x4*)(rec_ + 4 * cl); R.k = *(const LAS f32x4*)(rec_ + 64 + 4 * cl); R.r = *(const LAS f32x4*)(rec_ + 128 + 4 * cl); \
;                 if (RW) { R.kk = *(const LAS f32x4*)(rec_ + 192 + 4 * cl); R.kka = *(const LAS f32x4*)(rec_ + 256 + 4 * cl); } R.v = rec_[320 + crow]; } while (0)
;     ...
;             ScanRec A, B, C, E;
;             C_LD(A, 0); C_LD(B, 1);
	v_pk_mul_f32 v[172:173], v[180:181], v[114:115]
	v_pk_fma_f32 v[168:169], v[90:91], v[178:179], v[168:169]
	v_pk_fma_f32 v[172:173], v[178:179], v[116:117], v[172:173]
	v_add_f32_e32 v170, v168, v169
	ds_write_b32 v159, v170 offset:18432
	v_add_f32_e32 v172, v172, v173
	ds_read_b128 v[80:83], v160 offset:28224
	ds_read_b128 v[84:87], v160 offset:28480
	v_add_f32_dpp v172, v172, v172 quad_perm:[1,0,3,2] row_mask:0xf bank_mask:0xf bound_ctrl:1
	v_pk_mul_f32 v[164:165], v[180:181], v[102:103]
	v_pk_mul_f32 v[166:167], v[178:179], v[104:105]
	v_add_f32_dpp v172, v172, v172 quad_perm:[2,3,0,1] row_mask:0xf bank_mask:0xf bound_ctrl:1
	ds_read_b128 v[88:91], v160 offset:28736
	ds_read_b128 v[92:95], v160 offset:28992
	v_add_f32_dpp v172, v172, v172 row_half_mirror row_mask:0xf bank_mask:0xf bound_ctrl:1
	v_pk_fma_f32 v[164:165], v[106:107], v[122:123], v[164:165] op_sel_hi:[1,0,1]
	v_pk_fma_f32 v[166:167], v[108:109], v[122:123], v[166:167] op_sel_hi:[1,0,1]
	v_add_f32_dpp v172, v172, v172 row_mirror row_mask:0xf bank_mask:0xf bound_ctrl:1
	ds_read_b128 v[96:99], v160 offset:29248
	ds_read_b32 v100, v161 offset:29504
	v_pk_fma_f32 v[180:181], v[118:119], v[172:173], v[164:165] op_sel_hi:[1,0,1] neg_lo:[0,1,0] neg_hi:[0,1,0]
	v_pk_fma_f32 v[178:179], v[120:121], v[172:173], v[166:167] op_sel_hi:[1,0,1] neg_lo:[0,1,0] neg_hi:[0,1,0]
	v_pk_mul_f32 v[168:169], v[110:111], v[180:181]
	s_waitcnt lgkmcnt(7)
	v_pk_mul_f32 v[162:163], v[180:181], v[194:195]
	v_pk_fma_f32 v[168:169], v[112:113], v[178:179], v[168:169]
	v_pk_fma_f32 v[162:163], v[178:179], v[196:197], v[162:163]
	v_add_f32_e32 v170, v168, v169
	ds_write_b32 v159, v170 offset:19456
	v_add_f32_e32 v162, v162, v163
	ds_read_b128 v[102:105], v160 offset:29568
	ds_read_b128 v[106:109], v160 offset:29824
	v_add_f32_dpp v162, v162, v162 quad_perm:[1,0,3,2] row_mask:0xf bank_mask:0xf bound_ctrl:1
	v_pk_mul_f32 v[164:165], v[180:181], v[182:183]
	v_pk_mul_f32 v[166:167], v[178:179], v[184:185]
	v_add_f32_dpp v162, v162, v162 quad_perm:[2,3,0,1] row_mask:0xf bank_mask:0xf bound_ctrl:1
	ds_read_b128 v[110:113], v160 offset:30080
	ds_read_b128 v[114:117], v160 offset:30336
	v_add_f32_dpp v162, v162, v162 row_half_mirror row_mask:0xf bank_mask:0xf bound_ctrl:1
	v_pk_fma_f32 v[164:165], v[186:187], v[202:203], v[164:165] op_sel_hi:[1,0,1]
	v_pk_fma_f32 v[166:167], v[188:189], v[202:203], v[166:167] op_sel_hi:[1,0,1]
	v_add_f32_dpp v162, v162, v162 row_mirror row_mask:0xf bank_mask:0xf bound_ctrl:1
	ds_read_b128 v[118:121], v160 offset:30592
	ds_read_b32 v122, v161 offset:30848
	v_pk_fma_f32 v[180:181], v[198:199], v[162:163], v[164:165] op_sel_hi:[1,0,1] neg_lo:[0,1,0] neg_hi:[0,1,0]
	v_pk_fma_f32 v[178:179], v[200:201], v[162:163], v[166:167] op_sel_hi:[1,0,1] neg_lo:[0,1,0] neg_hi:[0,1,0]
	v_pk_mul_f32 v[168:169], v[190:191], v[180:181]
	s_waitcnt lgkmcnt(7)
	v_pk_mul_f32 v[172:173], v[180:181], v[92:93]
	v_pk_fma_f32 v[168:169], v[192:193], v[178:179], v[168:169]
	v_pk_fma_f32 v[172:173], v[178:179], v[94:95], v[172:173]
	v_add_f32_e32 v170, v168, v169
	ds_write_b32 v159, v170 offset:20480
	v_add_f32_e32 v172, v172, v173
	ds_read_b128 v[182:185], v160 offset:30912
	ds_read_b128 v[186:189], v160 offset:31168
	v_add_f32_dpp v172, v172, v172 quad_perm:[1,0,3,2] row_mask:0xf bank_mask:0xf bound_ctrl:1
	v_pk_mul_f32 v[164:165], v[180:181], v[80:81]
	v_pk_mul_f32 v[166:167], v[178:179], v[82:83]
	v_add_f32_dpp v172, v172, v172 quad_perm:[2,3,0,1] row_mask:0xf bank_mask:0xf bound_ctrl:1
	ds_read_b128 v[190:193], v160 offset:31424
	ds_read_b128 v[194:197], v160 offset:31680
	v_add_f32_dpp v172, v172, v172 row_half_mirror row_mask:0xf bank_mask:0xf bound_ctrl:1
	v_pk_fma_f32 v[164:165], v[84:85], v[100:101], v[164:165] op_sel_hi:[1,0,1]
	v_pk_fma_f32 v[166:167], v[86:87], v[100:101], v[166:167] op_sel_hi:[1,0,1]
	v_add_f32_dpp v172, v172, v172 row_mirror row_mask:0xf bank_mask:0xf bound_ctrl:1
	ds_read_b128 v[198:201], v160 offset:31936
	ds_read_b32 v202, v161 offset:32192
	v_pk_fma_f32 v[180:181], v[96:97], v[172:173], v[164:165] op_sel_hi:[1,0,1] neg_lo:[0,1,0] neg_hi:[0,1,0]
	v_pk_fma_f32 v[178:179], v[98:99], v[172:173], v[166:167] op_sel_hi:[1,0,1] neg_lo:[0,1,0] neg_hi:[0,1,0]
	v_pk_mul_f32 v[168:169], v[88:89], v[180:181]
	s_waitcnt lgkmcnt(7)
	v_pk_mul_f32 v[162:163], v[180:181], v[114:115]
	v_pk_fma_f32 v[168:169], v[90:91], v[178:179], v[168:169]
	v_pk_fma_f32 v[162:163], v[178:179], v[116:117], v[162:163]
	v_add_f32_e32 v170, v168, v169
	ds_write_b32 v159, v170 offset:21504
	v_add_f32_e32 v162, v162, v163
	ds_read_b128 v[80:83], v160 offset:32256
	ds_read_b128 v[84:87], v160 offset:32512
	v_add_f32_dpp v162, v162, v162 quad_perm:[1,0,3,2] row_mask:0xf bank_mask:0xf bound_ctrl:1
	v_pk_mul_f32 v[164:165], v[180:181], v[102:103]
	v_pk_mul_f32 v[166:167], v[178:179], v[104:105]
	v_add_f32_dpp v162, v162, v162 quad_perm:[2,3,0,1] row_mask:0xf bank_mask:0xf bound_ctrl:1
	ds_read_b128 v[88:91], v160 offset:32768
	ds_read_b128 v[92:95], v160 offset:33024
	v_add_f32_dpp v162, v162, v162 row_half_mirror row_mask:0xf bank_mask:0xf bound_ctrl:1
	v_pk_fma_f32 v[164:165], v[106:107], v[122:123], v[164:165] op_sel_hi:[1,0,1]
	v_pk_fma_f32 v[166:167], v[108:109], v[122:123], v[166:167] op_sel_hi:[1,0,1]
	v_add_f32_dpp v162, v162, v162 row_mirror row_mask:0xf bank_mask:0xf bound_ctrl:1
	ds_read_b128 v[96:99], v160 offset:33280
	ds_read_b32 v100, v161 offset:33536
	v_pk_fma_f32 v[180:181], v[118:119], v[162:163], v[164:165] op_sel_hi:[1,0,1] neg_lo:[0,1,0] neg_hi:[0,1,0]
	v_pk_fma_f32 v[178:179], v[120:121], v[162:163], v[166:167] op_sel_hi:[1,0,1] neg_lo:[0,1,0] neg_hi:[0,1,0]
	v_pk_mul_f32 v[168:169], v[110:111], v[180:181]
	s_waitcnt lgkmcnt(7)
; #define C_LD(R, t) do { const LAS float* rec_ = cur + (t) * REC; R.w = *(const LAS f32x4*)(rec_ + 4 * cl); R.k = *(const LAS f32x4*)(rec_ + 64 + 4 * cl); R.r = *(const LAS f32x4*)(rec_ + 128 + 4 * cl); \
;                 if (RW) { R.kk = *(const LAS f32x4*)(rec_ + 192 + 4 * cl); R.kka = *(const LAS f32x4*)(rec_ + 256 + 4 * cl); } R.v = rec_[320 + crow]; } while (0)
;     ...
;             ScanRec A, B, C, E;
;             C_LD(A, 0); C_LD(B, 1);
	v_pk_mul_f32 v[172:173], v[180:181], v[194:195]
	v_pk_fma_f32 v[168:169], v[112:113], v[178:179], v[168:169]
	v_pk_fma_f32 v[172:173], v[178:179], v[196:197], v[172:173]
	v_add_f32_e32 v170, v168, v169
	ds_write_b32 v159, v170 offset:22528
	v_add_f32_e32 v172, v172, v173
	ds_read_b128 v[102:105], v160 offset:33600
	ds_read_b128 v[106:109], v160 offset:33856
	v_add_f32_dpp v172, v172, v172 quad_perm:[1,0,3,2] row_mask:0xf bank_mask:0xf bound_ctrl:1
	v_pk_mul_f32 v[164:165], v[180:181], v[182:183]
	v_pk_mul_f32 v[166:167], v[178:179], v[184:185]
	v_add_f32_dpp v172, v172, v172 quad_perm:[2,3,0,1] row_mask:0xf bank_mask:0xf bound_ctrl:1
	ds_read_b128 v[110:113], v160 offset:34112
	ds_read_b128 v[114:117], v160 offset:34368
	v_add_f32_dpp v172, v172, v172 row_half_mirror row_mask:0xf bank_mask:0xf bound_ctrl:1
	v_pk_fma_f32 v[164:165], v[186:187], v[202:203], v[164:165] op_sel_hi:[1,0,1]
	v_pk_fma_f32 v[166:167], v[188:189], v[202:203], v[166:167] op_sel_hi:[1,0,1]
	v_add_f32_dpp v172, v172, v172 row_mirror row_mask:0xf bank_mask:0xf bound_ctrl:1
	ds_read_b128 v[118:121], v160 offset:34624
	ds_read_b32 v122, v161 offset:34880
	v_pk_fma_f32 v[180:181], v[198:199], v[172:173], v[164:165] op_sel_hi:[1,0,1] neg_lo:[0,1,0] neg_hi:[0,1,0]
	v_pk_fma_f32 v[178:179], v[200:201], v[172:173], v[166:167] op_sel_hi:[1,0,1] neg_lo:[0,1,0] neg_hi:[0,1,0]
	v_pk_mul_f32 v[168:169], v[190:191], v[180:181]
	s_waitcnt lgkmcnt(7)
	v_pk_mul_f32 v[162:163], v[180:181], v[92:93]
	v_pk_fma_f32 v[168:169], v[192:193], v[178:179], v[168:169]
	v_pk_fma_f32 v[162:163], v[178:179], v[94:95], v[162:163]
	v_add_f32_e32 v170, v168, v169
	ds_write_b32 v159, v170 offset:23552
	v_add_f32_e32 v162, v162, v163
	ds_read_b128 v[182:185], v160 offset:34944
	ds_read_b128 v[186:189], v160 offset:35200
	v_add_f32_dpp v162, v162, v162 quad_perm:[1,0,3,2] row_mask:0xf bank_mask:0xf bound_ctrl:1
	v_pk_mul_f32 v[164:165], v[180:181], v[80:81]
	v_pk_mul_f32 v[166:167], v[178:179], v[82:83]
	v_add_f32_dpp v162, v162, v162 quad_perm:[2,3,0,1] row_mask:0xf bank_mask:0xf bound_ctrl:1
	ds_read_b128 v[190:193], v160 offset:35456
	ds_read_b128 v[194:197], v160 offset:35712
	v_add_f32_dpp v162, v162, v162 row_half_mirror row_mask:0xf bank_mask:0xf bound_ctrl:1
	v_pk_fma_f32 v[164:165], v[84:85], v[100:101], v[164:165] op_sel_hi:[1,0,1]
	v_pk_fma_f32 v[166:167], v[86:87], v[100:101], v[166:167] op_sel_hi:[1,0,1]
	v_add_f32_dpp v162, v162, v162 row_mirror row_mask:0xf bank_mask:0xf bound_ctrl:1
	ds_read_b128 v[198:201], v160 offset:35968
	ds_read_b32 v202, v161 offset:36224
	v_pk_fma_f32 v[180:181], v[96:97], v[162:163], v[164:165] op_sel_hi:[1,0,1] neg_lo:[0,1,0] neg_hi:[0,1,0]
	v_pk_fma_f32 v[178:179], v[98:99], v[162:163], v[166:167] op_sel_hi:[1,0,1] neg_lo:[0,1,0] neg_hi:[0,1,0]
	v_pk_mul_f32 v[168:169], v[88:89], v[180:181]
	s_waitcnt lgkmcnt(7)
	v_pk_mul_f32 v[172:173], v[180:181], v[114:115]
	v_pk_fma_f32 v[168:169], v[90:91], v[178:179], v[168:169]
	v_pk_fma_f32 v[172:173], v[178:179], v[116:117], v[172:173]
	v_add_f32_e32 v170, v168, v169
	ds_write_b32 v159, v170 offset:24576
	v_add_f32_e32 v172, v172, v173
	ds_read_b128 v[80:83], v160 offset:36288
	ds_read_b128 v[84:87], v160 offset:36544
	v_add_f32_dpp v172, v172, v172 quad_perm:[1,0,3,2] row_mask:0xf bank_mask:0xf bound_ctrl:1
	v_pk_mul_f32 v[164:165], v[180:181], v[102:103]
	v_pk_mul_f32 v[166:167], v[178:179], v[104:105]
	v_add_f32_dpp v172, v172, v172 quad_perm:[2,3,0,1] row_mask:0xf bank_mask:0xf bound_ctrl:1
	ds_read_b128 v[88:91], v160 offset:36800
	ds_read_b128 v[92:95], v160 offset:37056
	v_add_f32_dpp v172, v172, v172 row_half_mirror row_mask:0xf bank_mask:0xf bound_ctrl:1
	v_pk_fma_f32 v[164:165], v[106:107], v[122:123], v[164:165] op_sel_hi:[1,0,1]
	v_pk_fma_f32 v[166:167], v[108:109], v[122:123], v[166:167] op_sel_hi:[1,0,1]
	v_add_f32_dpp v172, v172, v172 row_mirror row_mask:0xf bank_mask:0xf bound_ctrl:1
	ds_read_b128 v[96:99], v160 offset:37312
	ds_read_b32 v100, v161 offset:37568
	v_pk_fma_f32 v[180:181], v[118:119], v[172:173], v[164:165] op_sel_hi:[1,0,1] neg_lo:[0,1,0] neg_hi:[0,1,0]
	v_pk_fma_f32 v[178:179], v[120:121], v[172:173], v[166:167] op_sel_hi:[1,0,1] neg_lo:[0,1,0] neg_hi:[0,1,0]
	v_pk_mul_f32 v[168:169], v[110:111], v[180:181]
	s_waitcnt lgkmcnt(7)
	v_pk_mul_f32 v[162:163], v[180:181], v[194:195]
	v_pk_fma_f32 v[168:169], v[112:113], v[178:179], v[168:169]
	v_pk_fma_f32 v[162:163], v[178:179], v[196:197], v[162:163]
	v_add_f32_e32 v170, v168, v169
	ds_write_b32 v159, v170 offset:25600
	v_add_f32_e32 v162, v162, v163
	ds_read_b128 v[102:105], v160 offset:37632
	ds_read_b128 v[106:109], v160 offset:37888
	v_add_f32_dpp v162, v162, v162 quad_perm:[1,0,3,2] row_mask:0xf bank_mask:0xf bound_ctrl:1
	v_pk_mul_f32 v[164:165], v[180:181], v[182:183]
	v_pk_mul_f32 v[166:167], v[178:179], v[184:185]
	v_add_f32_dpp v162, v162, v162 quad_perm:[2,3,0,1] row_mask:0xf bank_mask:0xf bound_ctrl:1
	ds_read_b128 v[110:113], v160 offset:38144
	ds_read_b128 v[114:117], v160 offset:38400
	v_add_f32_dpp v162, v162, v162 row_half_mirror row_mask:0xf bank_mask:0xf bound_ctrl:1
	v_pk_fma_f32 v[164:165], v[186:187], v[202:203], v[164:165] op_sel_hi:[1,0,1]
	v_pk_fma_f32 v[166:167], v[188:189], v[202:203], v[166:167] op_sel_hi:[1,0,1]
	v_add_f32_dpp v162, v162, v162 row_mirror row_mask:0xf bank_mask:0xf bound_ctrl:1
	ds_read_b128 v[118:121], v160 offset:38656
	ds_read_b32 v122, v161 offset:38912
	v_pk_fma_f32 v[180:181], v[198:199], v[162:163], v[164:165] op_sel_hi:[1,0,1] neg_lo:[0,1,0] neg_hi:[0,1,0]
	v_pk_fma_f32 v[178:179], v[200:201], v[162:163], v[166:167] op_sel_hi:[1,0,1] neg_lo:[0,1,0] neg_hi:[0,1,0]
	v_pk_mul_f32 v[168:169], v[190:191], v[180:181]
	s_waitcnt lgkmcnt(7)
; #define C_LD(R, t) do { const LAS float* rec_ = cur + (t) * REC; R.w = *(const LAS f32x4*)(rec_ + 4 * cl); R.k = *(const LAS f32x4*)(rec_ + 64 + 4 * cl); R.r = *(const LAS f32x4*)(rec_ + 128 + 4 * cl); \
;                 if (RW) { R.kk = *(const LAS f32x4*)(rec_ + 192 + 4 * cl); R.kka = *(const LAS f32x4*)(rec_ + 256 + 4 * cl); } R.v = rec_[320 + crow]; } while (0)
; #define C_8(t) do { C_LD(C, (t) + 2); C_STEP(A, (t)); C_LD(E, (t) + 3); C_STEP(B, (t) + 1); C_LD(A, (t) + 4); C_STEP(C, (t) + 2); C_LD(B, (t) + 5); C_STEP(E, (t) + 3); \
;                     C_LD(C, (t) + 6); C_STEP(A, (t) + 4); C_LD(E, (t) + 7); C_STEP(B, (t) + 5); C_LD(A, (t) + 8); C_STEP(C, (t) + 6); C_LD(B, (t) + 9); C_STEP(E, (t) + 7); } while (0)
;     ...
;             ScanRec A, B, C, E;
;             C_LD(A, 0); C_LD(B, 1);
;     ...
;             C_8(0);
;             if (cd.nv > 8) { C_8(8); C_8(16); C_8(24); }
	v_pk_mul_f32 v[172:173], v[180:181], v[92:93]
	v_pk_fma_f32 v[168:169], v[192:193], v[178:179], v[168:169]
	v_pk_fma_f32 v[172:173], v[178:179], v[94:95], v[172:173]
	v_add_f32_e32 v170, v168, v169
	ds_write_b32 v159, v170 offset:26624
	v_add_f32_e32 v172, v172, v173
	ds_read_b128 v[182:185], v160 offset:38976
	ds_read_b128 v[186:189], v160 offset:39232
	v_add_f32_dpp v172, v172, v172 quad_perm:[1,0,3,2] row_mask:0xf bank_mask:0xf bound_ctrl:1
	v_pk_mul_f32 v[164:165], v[180:181], v[80:81]
	v_pk_mul_f32 v[166:167], v[178:179], v[82:83]
	v_add_f32_dpp v172, v172, v172 quad_perm:[2,3,0,1] row_mask:0xf bank_mask:0xf bound_ctrl:1
	ds_read_b128 v[190:193], v160 offset:39488
	ds_read_b128 v[194:197], v160 offset:39744
	v_add_f32_dpp v172, v172, v172 row_half_mirror row_mask:0xf bank_mask:0xf bound_ctrl:1
	v_pk_fma_f32 v[164:165], v[84:85], v[100:101], v[164:165] op_sel_hi:[1,0,1]
	v_pk_fma_f32 v[166:167], v[86:87], v[100:101], v[166:167] op_sel_hi:[1,0,1]
	v_add_f32_dpp v172, v172, v172 row_mirror row_mask:0xf bank_mask:0xf bound_ctrl:1
	ds_read_b128 v[198:201], v160 offset:40000
	ds_read_b32 v202, v161 offset:40256
	v_pk_fma_f32 v[180:181], v[96:97], v[172:173], v[164:165] op_sel_hi:[1,0,1] neg_lo:[0,1,0] neg_hi:[0,1,0]
	v_pk_fma_f32 v[178:179], v[98:99], v[172:173], v[166:167] op_sel_hi:[1,0,1] neg_lo:[0,1,0] neg_hi:[0,1,0]
	v_pk_mul_f32 v[168:169], v[88:89], v[180:181]
	s_waitcnt lgkmcnt(7)
	v_pk_mul_f32 v[162:163], v[180:181], v[114:115]
	v_pk_fma_f32 v[168:169], v[90:91], v[178:179], v[168:169]
	v_pk_fma_f32 v[162:163], v[178:179], v[116:117], v[162:163]
	v_add_f32_e32 v170, v168, v169
	ds_write_b32 v159, v170 offset:27648
	v_add_f32_e32 v162, v162, v163
	ds_read_b128 v[80:83], v160 offset:40320
	ds_read_b128 v[84:87], v160 offset:40576
	v_add_f32_dpp v162, v162, v162 quad_perm:[1,0,3,2] row_mask:0xf bank_mask:0xf bound_ctrl:1
	v_pk_mul_f32 v[164:165], v[180:181], v[102:103]
	v_pk_mul_f32 v[166:167], v[178:179], v[104:105]
	v_add_f32_dpp v162, v162, v162 quad_perm:[2,3,0,1] row_mask:0xf bank_mask:0xf bound_ctrl:1
	ds_read_b128 v[88:91], v160 offset:40832
	ds_read_b128 v[92:95], v160 offset:41088
	v_add_f32_dpp v162, v162, v162 row_half_mirror row_mask:0xf bank_mask:0xf bound_ctrl:1
	v_pk_fma_f32 v[164:165], v[106:107], v[122:123], v[164:165] op_sel_hi:[1,0,1]
	v_pk_fma_f32 v[166:167], v[108:109], v[122:123], v[166:167] op_sel_hi:[1,0,1]
	v_add_f32_dpp v162, v162, v162 row_mirror row_mask:0xf bank_mask:0xf bound_ctrl:1
	ds_read_b128 v[96:99], v160 offset:41344
	ds_read_b32 v100, v161 offset:41600
	v_pk_fma_f32 v[180:181], v[118:119], v[162:163], v[164:165] op_sel_hi:[1,0,1] neg_lo:[0,1,0] neg_hi:[0,1,0]
	v_pk_fma_f32 v[178:179], v[120:121], v[162:163], v[166:167] op_sel_hi:[1,0,1] neg_lo:[0,1,0] neg_hi:[0,1,0]
	v_pk_mul_f32 v[168:169], v[110:111], v[180:181]
	s_waitcnt lgkmcnt(7)
	v_pk_mul_f32 v[172:173], v[180:181], v[194:195]
	v_pk_fma_f32 v[168:169], v[112:113], v[178:179], v[168:169]
	v_pk_fma_f32 v[172:173], v[178:179], v[196:197], v[172:173]
	v_add_f32_e32 v170, v168, v169
	ds_write_b32 v159, v170 offset:28672
	v_add_f32_e32 v172, v172, v173
	ds_read_b128 v[102:105], v160 offset:41664
	ds_read_b128 v[106:109], v160 offset:41920
	v_add_f32_dpp v172, v172, v172 quad_perm:[1,0,3,2] row_mask:0xf bank_mask:0xf bound_ctrl:1
	v_pk_mul_f32 v[164:165], v[180:181], v[182:183]
	v_pk_mul_f32 v[166:167], v[178:179], v[184:185]
	v_add_f32_dpp v172, v172, v172 quad_perm:[2,3,0,1] row_mask:0xf bank_mask:0xf bound_ctrl:1
	ds_read_b128 v[110:113], v160 offset:42176
	ds_read_b128 v[114:117], v160 offset:42432
	v_add_f32_dpp v172, v172, v172 row_half_mirror row_mask:0xf bank_mask:0xf bound_ctrl:1
	v_pk_fma_f32 v[164:165], v[186:187], v[202:203], v[164:165] op_sel_hi:[1,0,1]
	v_pk_fma_f32 v[166:167], v[188:189], v[202:203], v[166:167] op_sel_hi:[1,0,1]
	v_add_f32_dpp v172, v172, v172 row_mirror row_mask:0xf bank_mask:0xf bound_ctrl:1
	ds_read_b128 v[118:121], v160 offset:42688
	ds_read_b32 v122, v161 offset:42944
	v_pk_fma_f32 v[180:181], v[198:199], v[172:173], v[164:165] op_sel_hi:[1,0,1] neg_lo:[0,1,0] neg_hi:[0,1,0]
	v_pk_fma_f32 v[178:179], v[200:201], v[172:173], v[166:167] op_sel_hi:[1,0,1] neg_lo:[0,1,0] neg_hi:[0,1,0]
	v_pk_mul_f32 v[168:169], v[190:191], v[180:181]
	s_waitcnt lgkmcnt(7)
	v_pk_mul_f32 v[162:163], v[180:181], v[92:93]
	v_pk_fma_f32 v[168:169], v[192:193], v[178:179], v[168:169]
	v_pk_fma_f32 v[162:163], v[178:179], v[94:95], v[162:163]
	v_add_f32_e32 v170, v168, v169
	ds_write_b32 v159, v170 offset:29696
	v_add_f32_e32 v162, v162, v163
	s_nop 1
	v_add_f32_dpp v162, v162, v162 quad_perm:[1,0,3,2] row_mask:0xf bank_mask:0xf bound_ctrl:1
	v_pk_mul_f32 v[164:165], v[180:181], v[80:81]
	v_pk_mul_f32 v[166:167], v[178:179], v[82:83]
	v_add_f32_dpp v162, v162, v162 quad_perm:[2,3,0,1] row_mask:0xf bank_mask:0xf bound_ctrl:1
	s_nop 1
	v_add_f32_dpp v162, v162, v162 row_half_mirror row_mask:0xf bank_mask:0xf bound_ctrl:1
	v_pk_fma_f32 v[164:165], v[84:85], v[100:101], v[164:165] op_sel_hi:[1,0,1]
	v_pk_fma_f32 v[166:167], v[86:87], v[100:101], v[166:167] op_sel_hi:[1,0,1]
	v_add_f32_dpp v162, v162, v162 row_mirror row_mask:0xf bank_mask:0xf bound_ctrl:1
	s_nop 1
	v_pk_fma_f32 v[180:181], v[96:97], v[162:163], v[164:165] op_sel_hi:[1,0,1] neg_lo:[0,1,0] neg_hi:[0,1,0]
	v_pk_fma_f32 v[178:179], v[98:99], v[162:163], v[166:167] op_sel_hi:[1,0,1] neg_lo:[0,1,0] neg_hi:[0,1,0]
	v_pk_mul_f32 v[168:169], v[88:89], v[180:181]
	s_waitcnt lgkmcnt(1)
	v_pk_mul_f32 v[172:173], v[180:181], v[114:115]
	v_pk_fma_f32 v[168:169], v[90:91], v[178:179], v[168:169]
	v_pk_fma_f32 v[172:173], v[178:179], v[116:117], v[172:173]
	v_add_f32_e32 v170, v168, v169
	ds_write_b32 v159, v170 offset:30720
	v_add_f32_e32 v172, v172, v173
	s_nop 1
	v_add_f32_dpp v172, v172, v172 quad_perm:[1,0,3,2] row_mask:0xf bank_mask:0xf bound_ctrl:1
	v_pk_mul_f32 v[164:165], v[180:181], v[102:103]
	v_pk_mul_f32 v[166:167], v[178:179], v[104:105]
	v_add_f32_dpp v172, v172, v172 quad_perm:[2,3,0,1] row_mask:0xf bank_mask:0xf bound_ctrl:1
	s_nop 1
	v_add_f32_dpp v172, v172, v172 row_half_mirror row_mask:0xf bank_mask:0xf bound_ctrl:1
	v_pk_fma_f32 v[164:165], v[106:107], v[122:123], v[164:165] op_sel_hi:[1,0,1]
	v_pk_fma_f32 v[166:167], v[108:109], v[122:123], v[166:167] op_sel_hi:[1,0,1]
	v_add_f32_dpp v172, v172, v172 row_mirror row_mask:0xf bank_mask:0xf bound_ctrl:1
	s_nop 1
	v_pk_fma_f32 v[180:181], v[118:119], v[172:173], v[164:165] op_sel_hi:[1,0,1] neg_lo:[0,1,0] neg_hi:[0,1,0]
	v_pk_fma_f32 v[178:179], v[120:121], v[172:173], v[166:167] op_sel_hi:[1,0,1] neg_lo:[0,1,0] neg_hi:[0,1,0]
	v_pk_mul_f32 v[168:169], v[110:111], v[180:181]
	s_nop 0
	v_pk_fma_f32 v[168:169], v[112:113], v[178:179], v[168:169]
	s_nop 0
	v_add_f32_e32 v170, v168, v169
	ds_write_b32 v159, v170 offset:31744
	v_mov_b32_e32 v80, v180
	v_mov_b32_e32 v81, v181
	v_mov_b32_e32 v82, v178
	v_mov_b32_e32 v83, v179
